# phase 3 tail: all 16 packed row-sum adds split into scalar v_add_f32 pairs (same operands and order)
# baseline (speedup 1.0000x reference)
; __device__ __forceinline__ void attn_tile(const bool BAND, AttnSmem& sm, u16* Qg, int qtok0, int hd, int nw, const u16* __restrict__ Kg, ...
;     ...
; #pragma unroll
;         for (int i = 0; i < 8; i++) { const f32v2 t2 = {pv[2 * i], pv[2 * i + 1]}; ls2 += t2; }
; #pragma unroll
;         for (int st = 0; st < 2; st++) {
;           union { uint32_t u[4]; bf16x8 b; } pf;
; #pragma unroll
;           for (int j = 0; j < 4; j++) pf.u[j] = pack2(pv[8 * st + 2 * j], pv[8 * st + 2 * j + 1]);
;           union { uint2 u[2]; bf16x8 b; } v0, v1;
;           const int kc = sb * 32 + 16 * st + 4 * h;
;           v0.u[0] = *(const uint2*)&sm.VT[cur][r][kc];
;           v0.u[1] = *(const uint2*)&sm.VT[cur][r][kc + 8];
;           v1.u[0] = *(const uint2*)&sm.VT[cur][32 + r][kc];
;           v1.u[1] = *(const uint2*)&sm.VT[cur][32 + r][kc + 8];
;           o0 = mfma32(v0.b, pf.b, o0);
;           o1 = mfma32(v1.b, pf.b, o1);
;         }
.Lp3_tail:
	v_add_f32_e32 v34, v134, v34
	v_add_f32_e32 v35, v135, v35
	v_cvt_pk_bf16_f32 v70, v50, v51
	v_add_f32_e32 v34, v36, v34
	v_add_f32_e32 v35, v37, v35
	v_cvt_pk_bf16_f32 v71, v52, v53
	v_add_f32_e32 v34, v38, v34
	v_add_f32_e32 v35, v39, v35
	v_cvt_pk_bf16_f32 v72, v54, v55
	v_add_f32_e32 v34, v40, v34
	v_add_f32_e32 v35, v41, v35
	v_cvt_pk_bf16_f32 v73, v56, v57
	v_add_f32_e32 v34, v42, v34
	v_add_f32_e32 v35, v43, v35
	v_cvt_pk_bf16_f32 v40, v62, v63
	v_add_f32_e32 v38, v44, v34
	v_add_f32_e32 v39, v45, v35
	s_waitcnt lgkmcnt(3)
	v_mfma_f32_32x32x16_bf16 v[2:17], v[212:215], v[70:73], v[2:17]
	v_add_f32_e32 v38, v46, v38
	v_add_f32_e32 v39, v47, v39
	v_cvt_pk_bf16_f32 v41, v64, v65
	v_add_f32_e32 v46, v48, v38
	v_add_f32_e32 v47, v49, v39
	v_cvt_pk_bf16_f32 v38, v58, v59
	v_cvt_pk_bf16_f32 v39, v60, v61
	s_waitcnt lgkmcnt(2)
	v_mfma_f32_32x32x16_bf16 v[18:33], v[216:219], v[70:73], v[18:33]
	s_waitcnt lgkmcnt(1)
	v_mfma_f32_32x32x16_bf16 v[2:17], v[220:223], v[38:41], v[2:17]
	v_add_f32_e32 v34, v46, v50
	v_add_f32_e32 v35, v47, v51
	v_add_f32_e32 v34, v52, v34
	v_add_f32_e32 v35, v53, v35
	v_add_f32_e32 v34, v54, v34
	v_add_f32_e32 v35, v55, v35
	v_add_f32_e32 v34, v56, v34
	v_add_f32_e32 v35, v57, v35
	s_waitcnt lgkmcnt(0)
	v_mfma_f32_32x32x16_bf16 v[18:33], v[224:227], v[38:41], v[18:33]
	v_add_f32_e32 v34, v58, v34
	v_add_f32_e32 v35, v59, v35
	v_add_f32_e32 v34, v60, v34
	v_add_f32_e32 v35, v61, v35
	v_add_f32_e32 v34, v62, v34
	v_add_f32_e32 v35, v63, v35
	v_add_f32_e32 v134, v64, v34
	v_add_f32_e32 v135, v65, v35
